# v20 + gate phase staging tile XOR-swizzled (token column ^ 2*((row>>5)&3)): LDS read conflicts 8-way -> 2-way
# baseline (speedup 1.0000x reference)
; DI void phase_gate(const Params& p, int ch) {
;     ...
;   float w0[3][8], b0[8];
;   { const int c0 = ch * 256 + (tid & 31) * 8;
; #pragma unroll
;     for (int i = 0; i < 8; ++i) { b0[i] = cb[c0 + i];
; #pragma unroll
;       for (int t = 0; t < 3; ++t) w0[t][i] = cw[t * 6144 + c0 + i]; } }
;   for (int it = blockIdx.x; it < T / 64; it += gridDim.x) {
;     const int tok0 = it * 64;
;     { int cl = tid >> 1, th = (tid & 1) * 32; const bft* s = yT + (size_t)cl * T + tok0 + th;
; #pragma unroll
;       for (int q = 0; q < 4; ++q) { u32x4 v = *(const u32x4*)(s + q * 8);
; #pragma unroll
;         for (int k = 0; k < 4; ++k) { tile[cl * 65 + th + q * 8 + 2 * k] = __uint_as_float(v[k] << 16); tile[cl * 65 + th + q * 8 + 2 * k + 1] = __uint_as_float(v[k] & 0xffff0000u); } } }
.LBB0_1706:
	s_or_b64 exec, exec, s[0:1]
	v_mov_b32_e32 v45, v180
	s_and_b64 vcc, exec, s[8:9]
	s_waitcnt lgkmcnt(0)
	s_barrier
	s_cbranch_vccnz .LBB0_1715
	v_lshlrev_b32_e32 v0, 3, v45
	v_and_b32_e32 v44, 0xf8, v0
	v_or_b32_e32 v0, s75, v44
	v_readlane_b32 s8, v240, 49
	v_lshlrev_b64 v[6:7], 2, v[0:1]
	v_readlane_b32 s9, v240, 50
	s_movk_i32 s0, 0x6000
	v_readlane_b32 s10, v240, 51
	v_lshl_add_u64 v[30:31], s[8:9], 0, v[6:7]
	v_add_co_u32_e32 v18, vcc, s0, v30
	s_mov_b32 s0, 0xc000
	s_nop 0
	v_addc_co_u32_e32 v19, vcc, 0, v31, vcc
	v_readlane_b32 s11, v240, 52
	v_add_co_u32_e32 v22, vcc, s0, v30
	s_mov_b64 s[0:1], 0x6000
	v_lshl_add_u64 v[10:11], s[10:11], 0, v[6:7]
	v_lshl_add_u64 v[26:27], v[30:31], 0, s[0:1]
	s_mov_b64 s[0:1], 0xc000
	global_load_dwordx4 v[2:5], v[10:11], off
	global_load_dwordx4 v[6:9], v[30:31], off
	s_nop 0
	global_load_dwordx4 v[10:13], v[10:11], off offset:16
	s_nop 0
	global_load_dwordx4 v[14:17], v[30:31], off offset:16
	v_addc_co_u32_e32 v23, vcc, 0, v31, vcc
	v_lshl_add_u64 v[30:31], v[30:31], 0, s[0:1]
	global_load_dwordx4 v[18:21], v[18:19], off
	s_and_b32 s0, s75, 0x300
	global_load_dwordx4 v[22:25], v[22:23], off
	v_ashrrev_i32_e32 v0, 1, v45
	global_load_dwordx4 v[26:29], v[26:27], off offset:16
	v_mov_b64_e32 v[34:35], s[82:83]
	global_load_dwordx4 v[30:33], v[30:31], off offset:16
	s_lshl_b32 s8, s0, 1
	s_mov_b32 s0, 0x18000
	v_lshlrev_b32_e32 v36, 5, v45
	v_mad_i64_i32 v[34:35], s[0:1], v0, s0, v[34:35]
	v_and_b32_e32 v36, 32, v36
	s_movk_i32 s1, 0x104
	v_mul_lo_u32 v37, v0, s1
	s_add_u32 s0, s68, s8
	v_lshlrev_b32_e32 v0, 1, v36
	v_mad_u32_u24 v56, v44, s1, 16
	v_bfe_u32 v224, v45, 5, 3
	v_bfe_u32 v225, v45, 2, 2
	v_lshlrev_b32_e32 v225, 1, v225
	v_xor_b32_e32 v225, v224, v225
	v_sub_u32_e32 v225, v225, v224
	v_lshl_add_u32 v56, v225, 2, v56
	s_addc_u32 s1, s69, 0
	v_lshl_add_u64 v[46:47], v[34:35], 0, v[0:1]
	v_lshlrev_b32_e32 v0, 1, v44
	v_lshlrev_b32_e32 v38, 2, v36
	v_lshl_add_u64 v[48:49], s[0:1], 0, v[0:1]
	v_readlane_b32 s0, v240, 10
	v_add3_u32 v57, 16, v37, v38
	v_bfe_u32 v218, v45, 6, 2
	v_xor_b32_e32 v219, 0, v218
	v_lshl_add_u32 v220, v219, 3, v57
	v_xor_b32_e32 v219, 1, v218
	v_lshl_add_u32 v221, v219, 3, v57
	v_xor_b32_e32 v219, 2, v218
	v_lshl_add_u32 v222, v219, 3, v57
	v_xor_b32_e32 v219, 3, v218
	v_lshl_add_u32 v223, v219, 3, v57
	s_mov_b32 s10, s0
	v_readlane_b32 s1, v240, 11
	s_waitcnt vmcnt(6)
	v_mov_b32_e32 v52, v7
	v_mov_b32_e32 v50, v3
	v_mov_b32_e32 v51, v5
	v_mov_b32_e32 v53, v9
	v_mov_b32_e32 v3, v4
	v_mov_b32_e32 v7, v8
	s_waitcnt vmcnt(5)
	v_mov_b32_e32 v4, v11
	v_mov_b32_e32 v5, v13
	s_waitcnt vmcnt(4)
	v_mov_b32_e32 v8, v15
	v_mov_b32_e32 v9, v17
	v_mov_b32_e32 v11, v12
	v_mov_b32_e32 v15, v16
	s_waitcnt vmcnt(3)
	v_mov_b32_e32 v12, v19
	v_mov_b32_e32 v13, v21
	s_waitcnt vmcnt(2)
	v_mov_b32_e32 v16, v23
	v_mov_b32_e32 v17, v25
	v_mov_b32_e32 v19, v20
	v_mov_b32_e32 v23, v24
	s_waitcnt vmcnt(1)
	v_mov_b32_e32 v20, v27
	v_mov_b32_e32 v21, v29
	s_waitcnt vmcnt(0)
	v_mov_b32_e32 v24, v31
	v_mov_b32_e32 v25, v33
	v_mov_b32_e32 v27, v28
	v_mov_b32_e32 v31, v32
	s_branch .LBB0_1709

; DI void phase_gate(const Params& p, int ch) {
;     ...
;   for (int it = blockIdx.x; it < T / 64; it += gridDim.x) {
;     const int tok0 = it * 64;
;     { int cl = tid >> 1, th = (tid & 1) * 32; const bft* s = yT + (size_t)cl * T + tok0 + th;
; #pragma unroll
;       for (int q = 0; q < 4; ++q) { u32x4 v = *(const u32x4*)(s + q * 8);
; #pragma unroll
;         for (int k = 0; k < 4; ++k) { tile[cl * 65 + th + q * 8 + 2 * k] = __uint_as_float(v[k] << 16); tile[cl * 65 + th + q * 8 + 2 * k + 1] = __uint_as_float(v[k] & 0xffff0000u); } } }
;     __syncthreads();
.LBB0_1709:
	s_lshl_b32 s0, s10, 6
	s_ashr_i32 s1, s0, 31
	v_lshl_add_u64 v[28:29], s[0:1], 1, v[46:47]
	global_load_dwordx4 v[32:35], v[28:29], off offset:48
	global_load_dwordx4 v[36:39], v[28:29], off offset:32
	global_load_dwordx4 v[40:43], v[28:29], off offset:16
	global_load_dwordx4 v[58:61], v[28:29], off
	s_mov_b32 s1, 0
	s_waitcnt vmcnt(0)
	v_lshlrev_b32_e32 v0, 16, v58
	v_and_b32_e32 v28, 0xffff0000, v58
	ds_write2_b32 v220, v0, v28 offset1:1
	v_lshlrev_b32_e32 v0, 16, v59
	v_and_b32_e32 v28, 0xffff0000, v59
	ds_write2_b32 v221, v0, v28 offset1:1
	v_lshlrev_b32_e32 v0, 16, v60
	v_and_b32_e32 v28, 0xffff0000, v60
	ds_write2_b32 v222, v0, v28 offset1:1
	v_lshlrev_b32_e32 v0, 16, v61
	v_and_b32_e32 v28, 0xffff0000, v61
	ds_write2_b32 v223, v0, v28 offset1:1
	v_lshlrev_b32_e32 v0, 16, v40
	v_and_b32_e32 v28, 0xffff0000, v40
	ds_write2_b32 v220, v0, v28 offset0:8 offset1:9
	v_lshlrev_b32_e32 v0, 16, v41
	v_and_b32_e32 v28, 0xffff0000, v41
	ds_write2_b32 v221, v0, v28 offset0:8 offset1:9
	v_lshlrev_b32_e32 v0, 16, v42
	v_and_b32_e32 v28, 0xffff0000, v42
	ds_write2_b32 v222, v0, v28 offset0:8 offset1:9
	v_lshlrev_b32_e32 v0, 16, v43
	v_and_b32_e32 v28, 0xffff0000, v43
	ds_write2_b32 v223, v0, v28 offset0:8 offset1:9
	v_lshlrev_b32_e32 v0, 16, v36
	v_and_b32_e32 v28, 0xffff0000, v36
	ds_write2_b32 v220, v0, v28 offset0:16 offset1:17
	v_lshlrev_b32_e32 v0, 16, v37
	v_and_b32_e32 v28, 0xffff0000, v37
	ds_write2_b32 v221, v0, v28 offset0:16 offset1:17
	v_lshlrev_b32_e32 v0, 16, v38
	v_and_b32_e32 v28, 0xffff0000, v38
	ds_write2_b32 v222, v0, v28 offset0:16 offset1:17
	v_lshlrev_b32_e32 v0, 16, v39
	v_and_b32_e32 v28, 0xffff0000, v39
	ds_write2_b32 v223, v0, v28 offset0:16 offset1:17
	v_lshlrev_b32_e32 v0, 16, v32
	v_and_b32_e32 v28, 0xffff0000, v32
	ds_write2_b32 v220, v0, v28 offset0:24 offset1:25
	v_lshlrev_b32_e32 v0, 16, v33
	v_and_b32_e32 v28, 0xffff0000, v33
	ds_write2_b32 v221, v0, v28 offset0:24 offset1:25
	v_lshlrev_b32_e32 v0, 16, v34
	v_and_b32_e32 v28, 0xffff0000, v34
	ds_write2_b32 v222, v0, v28 offset0:24 offset1:25
	v_lshlrev_b32_e32 v0, 16, v35
	v_and_b32_e32 v28, 0xffff0000, v35
	ds_write2_b32 v223, v0, v28 offset0:24 offset1:25
	s_waitcnt lgkmcnt(0)
	s_barrier
	s_branch .LBB0_1711
